# barrier: top counter placed in the same 128B line as the slot counters (each poller's own arrive atomic refreshes the line)
# baseline (speedup 1.0000x reference)
.LBB0_185:
	s_or_b64 exec, exec, s[10:11]
	s_waitcnt lgkmcnt(0)
	v_readlane_b32 s2, v253, 4
	v_ashrrev_i32_e32 v83, 31, v82
	v_readlane_b32 s3, v253, 5
	s_nop 1
	v_lshl_add_u64 v[2:3], s[2:3], 0, v[82:83]
	v_cmp_eq_u64_e32 vcc, 0, v[2:3]
	s_and_saveexec_b64 s[2:3], vcc
	s_cbranch_execz .LBB0_187
	v_mov_b32_e32 v1, 0x3b0b000
	v_mov_b32_e32 v4, 0
	global_store_dword v1, v4, s[0:1] offset:256
	global_store_dword v1, v4, s[0:1] offset:320
	global_store_dword v1, v4, s[0:1] offset:324
	global_store_dword v1, v4, s[0:1] offset:328
	global_store_dword v1, v4, s[0:1] offset:332
	global_store_dword v1, v4, s[0:1] offset:336
	global_store_dword v1, v4, s[0:1] offset:340
	global_store_dword v1, v4, s[0:1] offset:344
	global_store_dword v1, v4, s[0:1] offset:348
	global_store_dword v1, v4, s[0:1] offset:352

.Lgb_cdone_2:
	v_mov_b32_e32 v0, 0
	v_mov_b32_e32 v1, 1
	global_atomic_add v0, v1, s[100:101] offset:96

.Lgb_poll_2:
	global_load_dword v1, v0, s[100:101] offset:96 sc1
	s_waitcnt vmcnt(0)
	v_cmp_le_u32_e32 vcc, s98, v1
	s_cbranch_vccnz .Lgb_done_2
	s_sleep 6
	s_branch .Lgb_poll_2
